# instruction selection: packed v_pk_add_f32 / v_pk_fma_f32 in the forgetting-attention loops split into scalar pairs (bit-identical)
# speedup vs baseline: 1.0061x; 1.0003x over previous
.LBB0_564:
	v_lshl_add_u32 v33, v254, 4, 0
	v_add_u32_e32 v220, 0x10800, v33
	ds_read_b128 v[34:37], v220
	ds_read_b128 v[38:41], v220 offset:32
	s_xor_b64 s[58:59], s[4:5], -1
	s_cmp_eq_u32 s76, 0
	v_or_b32_e32 v33, s79, v205
	s_waitcnt lgkmcnt(1)
	s_nop 1
	v_add_f32_e32 v16, v16, v34
	v_add_f32_e32 v17, v17, v35
	v_add_f32_e32 v18, v18, v36
	v_add_f32_e32 v19, v19, v37
	ds_read_b128 v[34:37], v220 offset:128
	ds_read_b128 v[42:45], v220 offset:160
	s_waitcnt lgkmcnt(2)
	v_add_f32_e32 v20, v20, v38
	v_add_f32_e32 v21, v21, v39
	ds_read_b128 v[46:49], v220 offset:64
	ds_read_b128 v[50:53], v220 offset:96
	v_add_f32_e32 v22, v22, v40
	v_add_f32_e32 v23, v23, v41
	ds_read_b128 v[38:41], v220 offset:192
	ds_read_b128 v[54:57], v220 offset:224
	v_lshlrev_b32_e32 v200, 2, v254
	s_waitcnt lgkmcnt(3)
	v_add_f32_e32 v48, v26, v48
	v_add_f32_e32 v49, v27, v49
	s_waitcnt lgkmcnt(2)
	v_add_f32_e32 v52, v30, v52
	v_add_f32_e32 v53, v31, v53
	v_add_f32_e32 v46, v24, v46
	v_add_f32_e32 v47, v25, v47
	v_add_f32_e32 v50, v28, v50
	v_add_f32_e32 v51, v29, v51
	v_add_f32_e32 v24, v2, v36
	v_add_f32_e32 v25, v3, v37
	v_add_f32_e32 v2, v6, v44
	v_add_f32_e32 v3, v7, v45
	s_waitcnt lgkmcnt(1)
	v_add_f32_e32 v6, v10, v40
	v_add_f32_e32 v7, v11, v41
	s_waitcnt lgkmcnt(0)
	v_add_f32_e32 v10, v14, v56
	v_add_f32_e32 v11, v15, v57
	v_add_f32_e32 v14, v0, v34
	v_add_f32_e32 v15, v1, v35
	v_add_f32_e32 v4, v4, v42
	v_add_f32_e32 v5, v5, v43
	v_add_f32_e32 v8, v8, v38
	v_add_f32_e32 v9, v9, v39
	v_add_f32_e32 v12, v12, v54
	v_add_f32_e32 v13, v13, v55
	s_cselect_b64 s[4:5], -1, 0
	v_sub_u32_e32 v214, v33, v200
	v_cndmask_b32_e64 v27, v11, v201, s[4:5]
	v_cndmask_b32_e64 v26, v10, v201, s[4:5]
	v_cndmask_b32_e64 v7, v7, v201, s[4:5]
	v_cndmask_b32_e64 v6, v6, v201, s[4:5]
	v_cndmask_b32_e64 v3, v3, v201, s[4:5]
	v_cndmask_b32_e64 v2, v2, v201, s[4:5]
	v_cndmask_b32_e64 v1, v25, v201, s[4:5]
	v_cndmask_b32_e64 v0, v24, v201, s[4:5]
	v_cndmask_b32_e64 v31, v13, v201, s[4:5]
	v_cndmask_b32_e64 v30, v12, v201, s[4:5]
	v_cndmask_b32_e64 v29, v9, v201, s[4:5]
	v_cndmask_b32_e64 v28, v8, v201, s[4:5]
	v_cndmask_b32_e64 v25, v5, v201, s[4:5]
	v_cndmask_b32_e64 v24, v4, v201, s[4:5]
	v_cndmask_b32_e64 v5, v15, v201, s[4:5]
	v_cndmask_b32_e64 v4, v14, v201, s[4:5]
	v_cndmask_b32_e64 v15, v53, v201, s[4:5]
	v_cndmask_b32_e64 v14, v52, v201, s[4:5]
	v_cndmask_b32_e64 v11, v49, v201, s[4:5]
	v_cndmask_b32_e64 v10, v48, v201, s[4:5]
	v_cndmask_b32_e64 v13, v51, v201, s[4:5]
	v_cndmask_b32_e64 v12, v50, v201, s[4:5]
	v_cndmask_b32_e64 v9, v47, v201, s[4:5]
	s_andn2_b64 vcc, exec, s[58:59]
	v_cndmask_b32_e64 v8, v46, v201, s[4:5]
	s_cbranch_vccnz .LBB0_567
	s_cmp_le_i32 s61, s79
	s_cselect_b64 s[4:5], -1, 0
	s_add_i32 s14, s79, 0xc000001f
	s_cmp_gt_i32 s44, s14
	s_cselect_b64 s[14:15], -1, 0
	s_and_b64 s[4:5], s[4:5], s[14:15]
	s_and_b64 vcc, exec, s[4:5]
	s_cbranch_vccnz .LBB0_567
	v_subrev_u32_e32 v33, s44, v214
	v_cmp_gt_u32_e32 vcc, 2.0, v33
	v_add_u32_e32 v34, 0xbfffffe0, v33
	s_nop 0
	v_cndmask_b32_e32 v16, v201, v16, vcc
	v_cmp_lt_u32_e32 vcc, s71, v34
	v_add_u32_e32 v34, 0xbfffffff, v33
	s_nop 0
	v_cndmask_b32_e32 v4, v201, v4, vcc
	v_cmp_lt_u32_e32 vcc, s71, v34
	v_add_u32_e32 v34, 0xbfffffdf, v33
	s_nop 0
	v_cndmask_b32_e32 v17, v201, v17, vcc
	v_cmp_lt_u32_e32 vcc, s71, v34
	v_add_u32_e32 v34, 0xbffffffe, v33
	s_nop 0
	v_cndmask_b32_e32 v5, v201, v5, vcc
	v_cmp_lt_u32_e32 vcc, s71, v34
	v_add_u32_e32 v34, 0xbfffffde, v33
	s_nop 0
	v_cndmask_b32_e32 v18, v201, v18, vcc
	v_cmp_lt_u32_e32 vcc, s71, v34
	v_add_u32_e32 v34, 0xbffffffd, v33
	s_nop 0
	v_cndmask_b32_e32 v0, v201, v0, vcc
	v_cmp_lt_u32_e32 vcc, s71, v34
	v_add_u32_e32 v34, 0xbfffffdd, v33
	s_nop 0
	v_cndmask_b32_e32 v19, v201, v19, vcc
	v_cmp_lt_u32_e32 vcc, s71, v34
	v_add_u32_e32 v34, 0xbffffff8, v33
	s_nop 0
	v_cndmask_b32_e32 v1, v201, v1, vcc
	v_cmp_lt_u32_e32 vcc, s71, v34
	v_add_u32_e32 v34, 0xbfffffd8, v33
	s_nop 0
	v_cndmask_b32_e32 v20, v201, v20, vcc
	v_cmp_lt_u32_e32 vcc, s71, v34
	v_add_u32_e32 v34, 0xbffffff7, v33
	s_nop 0
	v_cndmask_b32_e32 v24, v201, v24, vcc
	v_cmp_lt_u32_e32 vcc, s71, v34
	v_add_u32_e32 v34, 0xbfffffd7, v33
	s_nop 0
	v_cndmask_b32_e32 v21, v201, v21, vcc
	v_cmp_lt_u32_e32 vcc, s71, v34
	v_add_u32_e32 v34, 0xbffffff6, v33
	s_nop 0
	v_cndmask_b32_e32 v25, v201, v25, vcc
	v_cmp_lt_u32_e32 vcc, s71, v34
	v_add_u32_e32 v34, 0xbfffffd6, v33
	s_nop 0
	v_cndmask_b32_e32 v22, v201, v22, vcc
	v_cmp_lt_u32_e32 vcc, s71, v34
	v_add_u32_e32 v34, 0xbffffff5, v33
	s_nop 0
	v_cndmask_b32_e32 v2, v201, v2, vcc
	v_cmp_lt_u32_e32 vcc, s71, v34
	v_add_u32_e32 v34, 0xbfffffd5, v33
	s_nop 0
	v_cndmask_b32_e32 v23, v201, v23, vcc
	v_cmp_lt_u32_e32 vcc, s71, v34
	v_add_u32_e32 v34, 0xbffffff0, v33
	s_nop 0
	v_cndmask_b32_e32 v3, v201, v3, vcc
	v_cmp_lt_u32_e32 vcc, s71, v34
	v_add_u32_e32 v34, 0xbfffffd0, v33
	s_nop 0
	v_cndmask_b32_e32 v8, v201, v8, vcc
	v_cmp_lt_u32_e32 vcc, s71, v34
	v_add_u32_e32 v34, 0xbfffffef, v33
	s_nop 0
	v_cndmask_b32_e32 v28, v201, v28, vcc
	v_cmp_lt_u32_e32 vcc, s71, v34
	v_add_u32_e32 v34, 0xbfffffcf, v33
	s_nop 0
	v_cndmask_b32_e32 v9, v201, v9, vcc
	v_cmp_lt_u32_e32 vcc, s71, v34
	v_add_u32_e32 v34, 0xbfffffee, v33
	s_nop 0
	v_cndmask_b32_e32 v29, v201, v29, vcc
	v_cmp_lt_u32_e32 vcc, s71, v34
	v_add_u32_e32 v34, 0xbfffffce, v33
	s_nop 0
	v_cndmask_b32_e32 v10, v201, v10, vcc
	v_cmp_lt_u32_e32 vcc, s71, v34
	v_add_u32_e32 v34, 0xbfffffed, v33
	s_nop 0
	v_cndmask_b32_e32 v6, v201, v6, vcc
	v_cmp_lt_u32_e32 vcc, s71, v34
	v_add_u32_e32 v34, 0xbfffffcd, v33
	s_nop 0
	v_cndmask_b32_e32 v11, v201, v11, vcc
	v_cmp_lt_u32_e32 vcc, s71, v34
	v_add_u32_e32 v34, 0xbfffffe8, v33
	s_nop 0
	v_cndmask_b32_e32 v7, v201, v7, vcc
	v_cmp_lt_u32_e32 vcc, s71, v34
	v_add_u32_e32 v34, 0xbfffffc8, v33
	s_nop 0
	v_cndmask_b32_e32 v12, v201, v12, vcc
	v_cmp_lt_u32_e32 vcc, s71, v34
	v_add_u32_e32 v34, 0xbfffffe7, v33
	s_nop 0
	v_cndmask_b32_e32 v30, v201, v30, vcc
	v_cmp_lt_u32_e32 vcc, s71, v34
	v_add_u32_e32 v34, 0xbfffffc7, v33
	s_nop 0
	v_cndmask_b32_e32 v13, v201, v13, vcc
	v_cmp_lt_u32_e32 vcc, s71, v34
	v_add_u32_e32 v34, 0xbfffffe6, v33
	s_nop 0
	v_cndmask_b32_e32 v31, v201, v31, vcc
	v_cmp_lt_u32_e32 vcc, s71, v34
	v_add_u32_e32 v34, 0xbfffffc6, v33
	s_nop 0
	v_cndmask_b32_e32 v14, v201, v14, vcc
	v_cmp_lt_u32_e32 vcc, s71, v34
	v_add_u32_e32 v34, 0xbfffffe5, v33
	v_add_u32_e32 v33, 0xbfffffc5, v33
	v_cndmask_b32_e32 v26, v201, v26, vcc
	v_cmp_lt_u32_e32 vcc, s71, v34
	s_nop 1
	v_cndmask_b32_e32 v15, v201, v15, vcc
	v_cmp_lt_u32_e32 vcc, s71, v33
	s_nop 1
	v_cndmask_b32_e32 v27, v201, v27, vcc

.LBB0_573:
	v_max_f32_e32 v33, 0xf149f2ca, v33
	v_cndmask_b32_e64 v178, v33, v189, s[4:5]
	v_and_b32_e32 v202, 63, v32
	v_mul_f32_e32 v32, 0xbe0293ee, v178
	v_fmamk_f32 v8, v8, 0x3e0293ee, v32
	v_exp_f32_e32 v162, v8
	v_sub_f32_e32 v8, 0xf149f2ca, v33
	v_mul_f32_e32 v8, 0x3e0293ee, v8
	v_exp_f32_e32 v8, v8
	v_fmamk_f32 v16, v16, 0x3e0293ee, v32
	v_fmamk_f32 v17, v17, 0x3e0293ee, v32
	v_fmamk_f32 v18, v18, 0x3e0293ee, v32
	v_fmamk_f32 v19, v19, 0x3e0293ee, v32
	v_fmamk_f32 v20, v20, 0x3e0293ee, v32
	v_fmamk_f32 v21, v21, 0x3e0293ee, v32
	v_fmamk_f32 v22, v22, 0x3e0293ee, v32
	v_fmamk_f32 v23, v23, 0x3e0293ee, v32
	v_fmamk_f32 v9, v9, 0x3e0293ee, v32
	v_fmamk_f32 v10, v10, 0x3e0293ee, v32
	v_fmamk_f32 v11, v11, 0x3e0293ee, v32
	v_fmamk_f32 v12, v12, 0x3e0293ee, v32
	v_fmamk_f32 v13, v13, 0x3e0293ee, v32
	v_fmamk_f32 v14, v14, 0x3e0293ee, v32
	v_fmamk_f32 v15, v15, 0x3e0293ee, v32
	v_lshlrev_b32_e32 v190, 4, v202
	v_exp_f32_e32 v173, v16
	v_exp_f32_e32 v175, v17
	v_exp_f32_e32 v171, v18
	v_exp_f32_e32 v174, v19
	v_exp_f32_e32 v169, v20
	v_exp_f32_e32 v172, v21
	v_exp_f32_e32 v168, v22
	v_exp_f32_e32 v170, v23
	v_exp_f32_e32 v165, v9
	v_exp_f32_e32 v161, v10
	v_exp_f32_e32 v163, v11
	v_exp_f32_e32 v160, v12
	v_exp_f32_e32 v167, v13
	v_exp_f32_e32 v164, v14
	v_exp_f32_e32 v166, v15
	v_fma_f32 v124, v0, s48, v32
	v_fma_f32 v125, v1, s48, v32
	v_lshlrev_b32_e32 v210, 3, v202
	v_and_b32_e32 v0, 0xc0, v190
	v_lshlrev_b32_e32 v1, 1, v202
	v_fma_f32 v120, v2, s48, v32
	v_fma_f32 v121, v3, s48, v32
	v_and_or_b32 v0, v210, 24, v0
	v_and_b32_e32 v1, 32, v1
	v_and_b32_e32 v2, 0x100, v210
	s_cmp_lg_u32 0, -1
	v_cndmask_b32_e64 v216, v8, 1.0, s[4:5]
	v_or3_b32 v0, v0, v1, v2
	s_cselect_b32 s4, 0, 0
	v_fma_f32 v112, v26, s48, v32
	v_fma_f32 v113, v27, s48, v32
	v_fma_f32 v114, v30, s48, v32
	v_fma_f32 v115, v31, s48, v32
	v_fma_f32 v116, v6, s48, v32
	v_fma_f32 v117, v7, s48, v32
	v_fma_f32 v118, v28, s48, v32
	v_fma_f32 v119, v29, s48, v32
	v_fma_f32 v122, v24, s48, v32
	v_fma_f32 v123, v25, s48, v32
	v_fma_f32 v126, v4, s48, v32
	v_fma_f32 v127, v5, s48, v32
	v_add_u32_e32 v213, s4, v0
	s_cmp_lt_i32 s82, 3
	v_cmp_gt_u32_e64 s[4:5], 32, v202
	v_lshl_add_u32 v212, v205, 2, s49
	s_waitcnt lgkmcnt(0)
	s_barrier
	s_cbranch_scc1 .LBB0_624
	v_lshlrev_b32_e32 v1, 4, v205
	v_and_b32_e32 v1, 0x70, v1
	v_or_b32_e32 v3, 32, v194
	v_or_b32_e32 v4, 64, v194
	v_or_b32_e32 v5, 0x60, v194
	v_xad_u32 v2, v194, v1, 0
	v_xad_u32 v3, v3, v1, 0
	v_xad_u32 v4, v4, v1, 0
	v_xad_u32 v1, v5, v1, 0
	v_lshlrev_b32_e32 v5, 2, v200
	v_add_u32_e32 v221, s73, v5
	v_add_u32_e32 v223, s49, v5
	v_add_u32_e32 v5, s67, v205
	v_sub_u32_e32 v5, v5, v200
	v_lshlrev_b32_e32 v0, 8, v205
	v_subrev_u32_e32 v5, s44, v5
	v_mov_b32_e32 v32, v193
	v_mov_b32_e32 v33, v193
	v_mov_b32_e32 v46, v193
	v_mov_b32_e32 v47, v193
	v_lshl_add_u64 v[196:197], s[8:9], 0, v[192:193]
	s_add_i32 s8, 0, 0x10800
	v_subrev_u32_e32 v224, s60, v5
	v_mov_b32_e32 v34, v193
	v_mov_b32_e32 v35, v193
	v_mov_b32_e32 v36, v193
	v_mov_b32_e32 v37, v193
	v_mov_b32_e32 v38, v193
	v_mov_b32_e32 v39, v193
	v_mov_b32_e32 v40, v193
	v_mov_b32_e32 v41, v193
	v_mov_b32_e32 v42, v193
	v_mov_b32_e32 v43, v193
	v_mov_b32_e32 v44, v193
	v_mov_b32_e32 v45, v193
	v_add_u32_e32 v225, v2, v0
	v_add_u32_e32 v226, v3, v0
	v_add_u32_e32 v227, v4, v0
	v_add_u32_e32 v228, v1, v0
	v_mov_b64_e32 v[62:63], v[46:47]
	v_mov_b64_e32 v[16:17], v[32:33]
	v_mov_b64_e32 v[0:1], v[32:33]
	v_lshl_add_u64 v[198:199], s[6:7], 0, v[192:193]
	v_cmp_gt_i32_e64 s[6:7], 64, v204
	s_add_i32 s88, s79, 0xc000001f
	v_lshl_add_u32 v222, v204, 2, s8
	v_mov_b32_e32 v217, 0
	s_mov_b64 s[56:57], 0
	s_mov_b32 s89, 6
	s_mov_b32 s90, s44
	v_mov_b64_e32 v[60:61], v[44:45]
	v_mov_b64_e32 v[58:59], v[42:43]
	v_mov_b64_e32 v[56:57], v[40:41]
	v_mov_b64_e32 v[54:55], v[38:39]
	v_mov_b64_e32 v[52:53], v[36:37]
	v_mov_b64_e32 v[50:51], v[34:35]
	v_mov_b64_e32 v[48:49], v[32:33]
	v_mov_b64_e32 v[18:19], v[34:35]
	v_mov_b64_e32 v[20:21], v[36:37]
	v_mov_b64_e32 v[22:23], v[38:39]
	v_mov_b64_e32 v[24:25], v[40:41]
	v_mov_b64_e32 v[26:27], v[42:43]
	v_mov_b64_e32 v[28:29], v[44:45]
	v_mov_b64_e32 v[30:31], v[46:47]
	v_mov_b64_e32 v[2:3], v[34:35]
	v_mov_b64_e32 v[4:5], v[36:37]
	v_mov_b64_e32 v[6:7], v[38:39]
	v_mov_b64_e32 v[8:9], v[40:41]
	v_mov_b64_e32 v[10:11], v[42:43]
	v_mov_b64_e32 v[12:13], v[44:45]
	v_mov_b64_e32 v[14:15], v[46:47]

.LBB0_588:
	ds_read_b128 v[98:101], v221
	ds_read_b128 v[102:105], v221 offset:32
	ds_read_b128 v[106:109], v221 offset:64
	ds_read_b128 v[110:113], v221 offset:96
	ds_read_b128 v[114:117], v221 offset:128
	ds_read_b128 v[118:121], v221 offset:160
	ds_read_b128 v[122:125], v221 offset:192
	ds_read_b128 v[180:183], v221 offset:224
	s_xor_b64 s[14:15], s[8:9], -1
	s_waitcnt lgkmcnt(7)
	v_add_f32_e32 v96, v82, v100
	v_add_f32_e32 v97, v83, v101
	s_waitcnt lgkmcnt(4)
	v_add_f32_e32 v82, v92, v110
	v_add_f32_e32 v83, v93, v111
	v_add_f32_e32 v92, v84, v102
	v_add_f32_e32 v93, v85, v103
	s_waitcnt lgkmcnt(0)
	v_add_f32_e32 v84, v76, v180
	v_add_f32_e32 v85, v77, v181
	v_cndmask_b32_e64 v76, 0, 1, s[14:15]
	v_add_f32_e32 v94, v94, v112
	v_add_f32_e32 v95, v95, v113
	v_add_f32_e32 v90, v90, v108
	v_add_f32_e32 v91, v91, v109
	v_add_f32_e32 v86, v86, v104
	v_add_f32_e32 v87, v87, v105
	v_add_f32_e32 v88, v88, v106
	v_add_f32_e32 v89, v89, v107
	v_add_f32_e32 v98, v80, v98
	v_add_f32_e32 v99, v81, v99
	v_add_f32_e32 v80, v78, v182
	v_add_f32_e32 v81, v79, v183
	v_add_f32_e32 v74, v74, v124
	v_add_f32_e32 v75, v75, v125
	v_add_f32_e32 v70, v70, v120
	v_add_f32_e32 v71, v71, v121
	v_add_f32_e32 v66, v66, v116
	v_add_f32_e32 v67, v67, v117
	v_add_f32_e32 v72, v72, v122
	v_add_f32_e32 v73, v73, v123
	v_add_f32_e32 v68, v68, v118
	v_add_f32_e32 v69, v69, v119
	v_cmp_ne_u32_e64 s[8:9], 1, v76
	s_andn2_b64 vcc, exec, s[14:15]
	v_add_f32_e32 v64, v64, v114
	v_add_f32_e32 v65, v65, v115
	s_cbranch_vccnz .LBB0_591
	s_cmp_le_i32 s61, s79
	s_cselect_b64 s[14:15], -1, 0
	s_cmp_gt_i32 s60, s88
	s_cselect_b64 s[24:25], -1, 0
	s_and_b64 s[14:15], s[14:15], s[24:25]
	s_and_b64 vcc, exec, s[14:15]
	s_cbranch_vccnz .LBB0_591
	v_add_u32_e32 v76, 0x4000007b, v224
	v_cmp_gt_u32_e32 vcc, 2.0, v76
	v_add_u32_e32 v76, 0x5b, v224
	s_nop 0
	v_cndmask_b32_e32 v98, v201, v98, vcc
	v_cmp_lt_u32_e32 vcc, s71, v76
	v_add_u32_e32 v76, 0x7a, v224
	s_nop 0
	v_cndmask_b32_e32 v64, v201, v64, vcc
	v_cmp_lt_u32_e32 vcc, s71, v76
	v_add_u32_e32 v76, 0x5a, v224
	s_nop 0
	v_cndmask_b32_e32 v99, v201, v99, vcc
	v_cmp_lt_u32_e32 vcc, s71, v76
	v_add_u32_e32 v76, 0x79, v224
	s_nop 0
	v_cndmask_b32_e32 v65, v201, v65, vcc
	v_cmp_lt_u32_e32 vcc, s71, v76
	v_add_u32_e32 v76, 0x59, v224
	s_nop 0
	v_cndmask_b32_e32 v96, v201, v96, vcc
	v_cmp_lt_u32_e32 vcc, s71, v76
	v_add_u32_e32 v76, 0x78, v224
	s_nop 0
	v_cndmask_b32_e32 v66, v201, v66, vcc
	v_cmp_lt_u32_e32 vcc, s71, v76
	v_add_u32_e32 v76, 0x58, v224
	s_nop 0
	v_cndmask_b32_e32 v97, v201, v97, vcc
	v_cmp_lt_u32_e32 vcc, s71, v76
	v_add_u32_e32 v76, 0x73, v224
	s_nop 0
	v_cndmask_b32_e32 v67, v201, v67, vcc
	v_cmp_lt_u32_e32 vcc, s71, v76
	v_add_u32_e32 v76, 0x53, v224
	s_nop 0
	v_cndmask_b32_e32 v92, v201, v92, vcc
	v_cmp_lt_u32_e32 vcc, s71, v76
	v_add_u32_e32 v76, 0x72, v224
	s_nop 0
	v_cndmask_b32_e32 v68, v201, v68, vcc
	v_cmp_lt_u32_e32 vcc, s71, v76
	v_add_u32_e32 v76, 0x52, v224
	s_nop 0
	v_cndmask_b32_e32 v93, v201, v93, vcc
	v_cmp_lt_u32_e32 vcc, s71, v76
	v_add_u32_e32 v76, 0x71, v224
	s_nop 0
	v_cndmask_b32_e32 v69, v201, v69, vcc
	v_cmp_lt_u32_e32 vcc, s71, v76
	v_add_u32_e32 v76, 0x51, v224
	s_nop 0
	v_cndmask_b32_e32 v86, v201, v86, vcc
	v_cmp_lt_u32_e32 vcc, s71, v76
	v_add_u32_e32 v76, 0x70, v224
	s_nop 0
	v_cndmask_b32_e32 v70, v201, v70, vcc
	v_cmp_lt_u32_e32 vcc, s71, v76
	v_add_u32_e32 v76, 0x50, v224
	s_nop 0
	v_cndmask_b32_e32 v87, v201, v87, vcc
	v_cmp_lt_u32_e32 vcc, s71, v76
	v_add_u32_e32 v76, 0x6b, v224
	s_nop 0
	v_cndmask_b32_e32 v71, v201, v71, vcc
	v_cmp_lt_u32_e32 vcc, s71, v76
	v_add_u32_e32 v76, 0x4b, v224
	s_nop 0
	v_cndmask_b32_e32 v88, v201, v88, vcc
	v_cmp_lt_u32_e32 vcc, s71, v76
	v_add_u32_e32 v76, 0x6a, v224
	s_nop 0
	v_cndmask_b32_e32 v72, v201, v72, vcc
	v_cmp_lt_u32_e32 vcc, s71, v76
	v_add_u32_e32 v76, 0x4a, v224
	s_nop 0
	v_cndmask_b32_e32 v89, v201, v89, vcc
	v_cmp_lt_u32_e32 vcc, s71, v76
	v_add_u32_e32 v76, 0x69, v224
	s_nop 0
	v_cndmask_b32_e32 v73, v201, v73, vcc
	v_cmp_lt_u32_e32 vcc, s71, v76
	v_add_u32_e32 v76, 0x49, v224
	s_nop 0
	v_cndmask_b32_e32 v90, v201, v90, vcc
	v_cmp_lt_u32_e32 vcc, s71, v76
	v_add_u32_e32 v76, 0x68, v224
	s_nop 0
	v_cndmask_b32_e32 v74, v201, v74, vcc
	v_cmp_lt_u32_e32 vcc, s71, v76
	v_add_u32_e32 v76, 0x48, v224
	s_nop 0
	v_cndmask_b32_e32 v91, v201, v91, vcc
	v_cmp_lt_u32_e32 vcc, s71, v76
	v_add_u32_e32 v76, 0x63, v224
	s_nop 0
	v_cndmask_b32_e32 v75, v201, v75, vcc
	v_cmp_lt_u32_e32 vcc, s71, v76
	v_add_u32_e32 v76, 0x43, v224
	s_nop 0
	v_cndmask_b32_e32 v82, v201, v82, vcc
	v_cmp_lt_u32_e32 vcc, s71, v76
	v_add_u32_e32 v76, 0x62, v224
	s_nop 0
	v_cndmask_b32_e32 v84, v201, v84, vcc
	v_cmp_lt_u32_e32 vcc, s71, v76
	v_add_u32_e32 v76, 0x42, v224
	s_nop 0
	v_cndmask_b32_e32 v83, v201, v83, vcc
	v_cmp_lt_u32_e32 vcc, s71, v76
	v_add_u32_e32 v76, 0x61, v224
	s_nop 0
	v_cndmask_b32_e32 v85, v201, v85, vcc
	v_cmp_lt_u32_e32 vcc, s71, v76
	v_add_u32_e32 v76, 0x41, v224
	s_nop 0
	v_cndmask_b32_e32 v94, v201, v94, vcc
	v_cmp_lt_u32_e32 vcc, s71, v76
	v_add_u32_e32 v76, 0x60, v224
	s_nop 0
	v_cndmask_b32_e32 v80, v201, v80, vcc
	v_cmp_lt_u32_e32 vcc, s71, v76
	v_add_u32_e32 v76, 64, v224
	s_nop 0
	v_cndmask_b32_e32 v95, v201, v95, vcc
	v_cmp_lt_u32_e32 vcc, s71, v76
	s_nop 1
	v_cndmask_b32_e32 v81, v201, v81, vcc

.LBB0_608:
	ds_read_b128 v[178:181], v220
	ds_read_b128 v[182:185], v220 offset:32
	ds_read_b128 v[186:189], v220 offset:64
	ds_read_b128 v[206:209], v220 offset:96
	ds_read_b128 v[236:239], v220 offset:128
	ds_read_b128 v[240:243], v220 offset:160
	ds_read_b128 v[244:247], v220 offset:192
	ds_read_b128 v[248:251], v220 offset:224
	s_waitcnt lgkmcnt(4)
	v_add_f32_e32 v126, v126, v208
	v_add_f32_e32 v127, v127, v209
	v_add_f32_e32 v122, v122, v188
	v_add_f32_e32 v123, v123, v189
	v_add_f32_e32 v118, v118, v184
	v_add_f32_e32 v119, v119, v185
	v_add_f32_e32 v176, v114, v180
	v_add_f32_e32 v177, v115, v181
	v_add_f32_e32 v114, v124, v206
	v_add_f32_e32 v115, v125, v207
	v_add_f32_e32 v120, v120, v186
	v_add_f32_e32 v121, v121, v187
	v_add_f32_e32 v116, v116, v182
	v_add_f32_e32 v117, v117, v183
	v_add_f32_e32 v112, v112, v178
	v_add_f32_e32 v113, v113, v179
	s_waitcnt lgkmcnt(0)
	v_add_f32_e32 v110, v110, v250
	v_add_f32_e32 v111, v111, v251
	v_add_f32_e32 v106, v106, v246
	v_add_f32_e32 v107, v107, v247
	v_add_f32_e32 v102, v102, v242
	v_add_f32_e32 v103, v103, v243
	v_add_f32_e32 v98, v98, v238
	v_add_f32_e32 v99, v99, v239
	v_add_f32_e32 v108, v108, v248
	v_add_f32_e32 v109, v109, v249
	v_add_f32_e32 v104, v104, v244
	v_add_f32_e32 v105, v105, v245
	v_add_f32_e32 v100, v100, v240
	v_add_f32_e32 v101, v101, v241
	s_andn2_b64 vcc, exec, s[60:61]
	v_add_f32_e32 v96, v96, v236
	v_add_f32_e32 v97, v97, v237
	s_cbranch_vccnz .LBB0_611
	s_cmp_le_i32 s93, s79
	s_cselect_b64 s[8:9], -1, 0
	s_cmp_gt_i32 s92, s88
	s_cselect_b64 s[14:15], -1, 0
	s_and_b64 s[8:9], s[8:9], s[14:15]
	s_and_b64 vcc, exec, s[8:9]
	s_cbranch_vccnz .LBB0_611
	v_add_u32_e32 v124, 0x4000003b, v224
	v_cmp_gt_u32_e32 vcc, 2.0, v124
	v_add_u32_e32 v124, 27, v224
	s_nop 0
	v_cndmask_b32_e32 v112, v201, v112, vcc
	v_cmp_lt_u32_e32 vcc, s71, v124
	v_add_u32_e32 v124, 58, v224
	s_nop 0
	v_cndmask_b32_e32 v96, v201, v96, vcc
	v_cmp_lt_u32_e32 vcc, s71, v124
	v_add_u32_e32 v124, 26, v224
	s_nop 0
	v_cndmask_b32_e32 v113, v201, v113, vcc
	v_cmp_lt_u32_e32 vcc, s71, v124
	v_add_u32_e32 v124, 57, v224
	s_nop 0
	v_cndmask_b32_e32 v97, v201, v97, vcc
	v_cmp_lt_u32_e32 vcc, s71, v124
	v_add_u32_e32 v124, 25, v224
	s_nop 0
	v_cndmask_b32_e32 v176, v201, v176, vcc
	v_cmp_lt_u32_e32 vcc, s71, v124
	v_add_u32_e32 v124, 56, v224
	s_nop 0
	v_cndmask_b32_e32 v98, v201, v98, vcc
	v_cmp_lt_u32_e32 vcc, s71, v124
	v_add_u32_e32 v124, 24, v224
	s_nop 0
	v_cndmask_b32_e32 v177, v201, v177, vcc
	v_cmp_lt_u32_e32 vcc, s71, v124
	v_add_u32_e32 v124, 51, v224
	s_nop 0
	v_cndmask_b32_e32 v99, v201, v99, vcc
	v_cmp_lt_u32_e32 vcc, s71, v124
	v_add_u32_e32 v124, 19, v224
	s_nop 0
	v_cndmask_b32_e32 v116, v201, v116, vcc
	v_cmp_lt_u32_e32 vcc, s71, v124
	v_add_u32_e32 v124, 50, v224
	s_nop 0
	v_cndmask_b32_e32 v100, v201, v100, vcc
	v_cmp_lt_u32_e32 vcc, s71, v124
	v_add_u32_e32 v124, 18, v224
	s_nop 0
	v_cndmask_b32_e32 v117, v201, v117, vcc
	v_cmp_lt_u32_e32 vcc, s71, v124
	v_add_u32_e32 v124, 49, v224
	s_nop 0
	v_cndmask_b32_e32 v101, v201, v101, vcc
	v_cmp_lt_u32_e32 vcc, s71, v124
	v_add_u32_e32 v124, 17, v224
	s_nop 0
	v_cndmask_b32_e32 v118, v201, v118, vcc
	v_cmp_lt_u32_e32 vcc, s71, v124
	v_add_u32_e32 v124, 48, v224
	s_nop 0
	v_cndmask_b32_e32 v102, v201, v102, vcc
	v_cmp_lt_u32_e32 vcc, s71, v124
	v_add_u32_e32 v124, 16, v224
	s_nop 0
	v_cndmask_b32_e32 v119, v201, v119, vcc
	v_cmp_lt_u32_e32 vcc, s71, v124
	v_add_u32_e32 v124, 43, v224
	s_nop 0
	v_cndmask_b32_e32 v103, v201, v103, vcc
	v_cmp_lt_u32_e32 vcc, s71, v124
	v_add_u32_e32 v124, 11, v224
	s_nop 0
	v_cndmask_b32_e32 v120, v201, v120, vcc
	v_cmp_lt_u32_e32 vcc, s71, v124
	v_add_u32_e32 v124, 42, v224
	s_nop 0
	v_cndmask_b32_e32 v104, v201, v104, vcc
	v_cmp_lt_u32_e32 vcc, s71, v124
	v_add_u32_e32 v124, 10, v224
	s_nop 0
	v_cndmask_b32_e32 v121, v201, v121, vcc
	v_cmp_lt_u32_e32 vcc, s71, v124
	v_add_u32_e32 v124, 41, v224
	s_nop 0
	v_cndmask_b32_e32 v105, v201, v105, vcc
	v_cmp_lt_u32_e32 vcc, s71, v124
	v_add_u32_e32 v124, 9, v224
	s_nop 0
	v_cndmask_b32_e32 v122, v201, v122, vcc
	v_cmp_lt_u32_e32 vcc, s71, v124
	v_add_u32_e32 v124, 40, v224
	s_nop 0
	v_cndmask_b32_e32 v106, v201, v106, vcc
	v_cmp_lt_u32_e32 vcc, s71, v124
	v_add_u32_e32 v124, 8, v224
	s_nop 0
	v_cndmask_b32_e32 v123, v201, v123, vcc
	v_cmp_lt_u32_e32 vcc, s71, v124
	v_add_u32_e32 v124, 35, v224
	s_nop 0
	v_cndmask_b32_e32 v107, v201, v107, vcc
	v_cmp_lt_u32_e32 vcc, s71, v124
	v_add_u32_e32 v124, 3, v224
	s_nop 0
	v_cndmask_b32_e32 v114, v201, v114, vcc
	v_cmp_lt_u32_e32 vcc, s71, v124
	v_add_u32_e32 v124, 34, v224
	s_nop 0
	v_cndmask_b32_e32 v108, v201, v108, vcc
	v_cmp_lt_u32_e32 vcc, s71, v124
	v_add_u32_e32 v124, 2, v224
	s_nop 0
	v_cndmask_b32_e32 v115, v201, v115, vcc
	v_cmp_lt_u32_e32 vcc, s71, v124
	v_add_u32_e32 v124, 33, v224
	s_nop 0
	v_cndmask_b32_e32 v109, v201, v109, vcc
	v_cmp_lt_u32_e32 vcc, s71, v124
	v_add_u32_e32 v124, 1, v224
	s_nop 0
	v_cndmask_b32_e32 v126, v201, v126, vcc
	v_cmp_lt_u32_e32 vcc, s71, v124
	v_add_u32_e32 v124, 32, v224
	s_nop 0
	v_cndmask_b32_e32 v110, v201, v110, vcc
	v_cmp_lt_u32_e32 vcc, s71, v124
	s_nop 1
	v_cndmask_b32_e32 v127, v201, v127, vcc
	v_cmp_lt_u32_e32 vcc, s71, v224
	s_nop 1
	v_cndmask_b32_e32 v111, v201, v111, vcc

.LBB0_622:
	v_cndmask_b32_e64 v178, v124, v232, s[8:9]
	v_mul_f32_e32 v180, 0xbe0293ee, v178
	v_mov_b32_e32 v181, v180
	v_fmamk_f32 v124, v112, 0x3e0293ee, v180
	v_fmamk_f32 v125, v113, 0x3e0293ee, v180
	s_waitcnt vmcnt(3)
	v_fmamk_f32 v160, v176, 0x3e0293ee, v180
	v_fmamk_f32 v161, v177, 0x3e0293ee, v180
	v_fmamk_f32 v162, v116, 0x3e0293ee, v180
	v_fmamk_f32 v163, v117, 0x3e0293ee, v180
	s_waitcnt vmcnt(2)
	v_fmamk_f32 v164, v118, 0x3e0293ee, v180
	v_fmamk_f32 v165, v119, 0x3e0293ee, v180
	v_fmamk_f32 v166, v120, 0x3e0293ee, v180
	v_fmamk_f32 v167, v121, 0x3e0293ee, v180
	v_fmamk_f32 v122, v122, 0x3e0293ee, v180
	v_fmamk_f32 v123, v123, 0x3e0293ee, v180
	v_fmamk_f32 v176, v114, 0x3e0293ee, v180
	v_fmamk_f32 v177, v115, 0x3e0293ee, v180
	v_fmamk_f32 v126, v126, 0x3e0293ee, v180
	v_fmac_f32_e32 v181, 0x3e0293ee, v127
	s_waitcnt vmcnt(0)
	v_exp_f32_e32 v173, v124
	v_exp_f32_e32 v175, v125
	v_exp_f32_e32 v171, v160
	v_exp_f32_e32 v174, v161
	v_exp_f32_e32 v169, v162
	v_exp_f32_e32 v172, v163
	v_exp_f32_e32 v168, v164
	v_exp_f32_e32 v170, v165
	v_exp_f32_e32 v162, v166
	v_exp_f32_e32 v165, v167
	v_exp_f32_e32 v161, v122
	v_exp_f32_e32 v163, v123
	v_exp_f32_e32 v160, v176
	v_exp_f32_e32 v167, v177
	v_exp_f32_e32 v164, v126
	v_exp_f32_e32 v166, v181
	v_fma_f32 v126, v96, s48, v180
	v_fma_f32 v127, v97, s48, v180
	v_add_f32_e32 v96, v229, v230
	v_fmac_f32_e32 v96, v217, v216
	v_add_f32_e32 v217, v234, v235
	s_add_i32 s8, s89, 2
	s_add_i32 s9, s89, -2
	v_fma_f32 v112, v110, s48, v180
	v_fma_f32 v113, v111, s48, v180
	v_fma_f32 v114, v108, s48, v180
	v_fma_f32 v115, v109, s48, v180
	v_fma_f32 v116, v106, s48, v180
	v_fma_f32 v117, v107, s48, v180
	v_fma_f32 v118, v104, s48, v180
	v_fma_f32 v119, v105, s48, v180
	v_fma_f32 v120, v102, s48, v180
	v_fma_f32 v121, v103, s48, v180
	v_fma_f32 v122, v100, s48, v180
	v_fma_f32 v123, v101, s48, v180
	v_fma_f32 v124, v98, s48, v180
	v_fma_f32 v125, v99, s48, v180
	v_fmac_f32_e32 v217, v96, v231
	s_cmp_ge_i32 s9, s82
	v_add_u32_e32 v224, 0xffffff80, v224
	s_waitcnt lgkmcnt(0)
	s_barrier
	s_cbranch_scc1 .LBB0_625
	s_mov_b32 s90, s92
	s_mov_b32 s89, s8
	v_mov_b32_e32 v216, v179
	s_branch .LBB0_575

.LBB0_651:
	v_add_f32_e32 v116, v176, v177
	s_andn2_b64 vcc, exec, s[6:7]
	v_fmac_f32_e32 v116, v216, v217
	s_cbranch_vccnz .LBB0_662
	v_lshl_add_u32 v112, v200, 2, 0
	v_add_u32_e32 v112, 0x10900, v112
	s_lshl_b32 s9, s78, 6
	ds_read_b128 v[118:121], v112
	ds_read_b128 v[122:125], v112 offset:32
	ds_read_b128 v[160:163], v112 offset:64
	ds_read_b128 v[164:167], v112 offset:96
	ds_read_b128 v[168:171], v112 offset:128
	ds_read_b128 v[172:175], v112 offset:160
	ds_read_b128 v[180:183], v112 offset:192
	ds_read_b128 v[184:187], v112 offset:224
	s_sub_i32 s8, s9, 64
	s_cmp_le_i32 s8, s80
	s_cselect_b64 s[6:7], -1, 0
	s_cmp_gt_i32 s9, s81
	s_cselect_b64 s[14:15], -1, 0
	s_and_b64 s[14:15], s[6:7], s[14:15]
	s_waitcnt lgkmcnt(7)
	v_add_f32_e32 v112, v66, v120
	v_add_f32_e32 v113, v67, v121
	s_waitcnt lgkmcnt(4)
	v_add_f32_e32 v66, v76, v164
	v_add_f32_e32 v67, v77, v165
	v_add_f32_e32 v76, v68, v122
	v_add_f32_e32 v77, v69, v123
	s_waitcnt lgkmcnt(0)
	v_add_f32_e32 v68, v92, v184
	v_add_f32_e32 v69, v93, v185
	v_cndmask_b32_e64 v92, 0, 1, s[14:15]
	v_add_f32_e32 v78, v78, v166
	v_add_f32_e32 v79, v79, v167
	v_add_f32_e32 v74, v74, v162
	v_add_f32_e32 v75, v75, v163
	v_add_f32_e32 v70, v70, v124
	v_add_f32_e32 v71, v71, v125
	v_add_f32_e32 v72, v72, v160
	v_add_f32_e32 v73, v73, v161
	v_add_f32_e32 v114, v64, v118
	v_add_f32_e32 v115, v65, v119
	v_add_f32_e32 v64, v94, v186
	v_add_f32_e32 v65, v95, v187
	v_add_f32_e32 v90, v90, v182
	v_add_f32_e32 v91, v91, v183
	v_add_f32_e32 v86, v86, v174
	v_add_f32_e32 v87, v87, v175
	v_add_f32_e32 v82, v82, v170
	v_add_f32_e32 v83, v83, v171
	v_add_f32_e32 v88, v88, v180
	v_add_f32_e32 v89, v89, v181
	v_add_f32_e32 v84, v84, v172
	v_add_f32_e32 v85, v85, v173
	v_cmp_ne_u32_e64 s[6:7], 1, v92
	s_andn2_b64 vcc, exec, s[14:15]
	v_add_f32_e32 v80, v80, v168
	v_add_f32_e32 v81, v81, v169
	s_cbranch_vccnz .LBB0_655
	s_add_i32 s9, s9, -1
	s_cmp_le_i32 s9, s79
	s_cselect_b64 s[14:15], -1, 0
	s_add_i32 s79, s79, 0xc000001f
	s_cmp_gt_i32 s8, s79
	s_cselect_b64 s[24:25], -1, 0
	s_and_b64 s[14:15], s[14:15], s[24:25]
	s_and_b64 vcc, exec, s[14:15]
	s_cbranch_vccnz .LBB0_655
	v_subrev_u32_e32 v92, s8, v214
	v_cmp_gt_u32_e32 vcc, 2.0, v92
	v_add_u32_e32 v93, 0xbfffffe0, v92
	s_nop 0
	v_cndmask_b32_e32 v114, v201, v114, vcc
	v_cmp_lt_u32_e32 vcc, s71, v93
	v_add_u32_e32 v93, 0xbfffffff, v92
	s_nop 0
	v_cndmask_b32_e32 v80, v201, v80, vcc
	v_cmp_lt_u32_e32 vcc, s71, v93
	v_add_u32_e32 v93, 0xbfffffdf, v92
	s_nop 0
	v_cndmask_b32_e32 v115, v201, v115, vcc
	v_cmp_lt_u32_e32 vcc, s71, v93
	v_add_u32_e32 v93, 0xbffffffe, v92
	s_nop 0
	v_cndmask_b32_e32 v81, v201, v81, vcc
	v_cmp_lt_u32_e32 vcc, s71, v93
	v_add_u32_e32 v93, 0xbfffffde, v92
	s_nop 0
	v_cndmask_b32_e32 v112, v201, v112, vcc
	v_cmp_lt_u32_e32 vcc, s71, v93
	v_add_u32_e32 v93, 0xbffffffd, v92
	s_nop 0
	v_cndmask_b32_e32 v82, v201, v82, vcc
	v_cmp_lt_u32_e32 vcc, s71, v93
	v_add_u32_e32 v93, 0xbfffffdd, v92
	s_nop 0
	v_cndmask_b32_e32 v113, v201, v113, vcc
	v_cmp_lt_u32_e32 vcc, s71, v93
	v_add_u32_e32 v93, 0xbffffff8, v92
	s_nop 0
	v_cndmask_b32_e32 v83, v201, v83, vcc
	v_cmp_lt_u32_e32 vcc, s71, v93
	v_add_u32_e32 v93, 0xbfffffd8, v92
	s_nop 0
	v_cndmask_b32_e32 v76, v201, v76, vcc
	v_cmp_lt_u32_e32 vcc, s71, v93
	v_add_u32_e32 v93, 0xbffffff7, v92
	s_nop 0
	v_cndmask_b32_e32 v84, v201, v84, vcc
	v_cmp_lt_u32_e32 vcc, s71, v93
	v_add_u32_e32 v93, 0xbfffffd7, v92
	s_nop 0
	v_cndmask_b32_e32 v77, v201, v77, vcc
	v_cmp_lt_u32_e32 vcc, s71, v93
	v_add_u32_e32 v93, 0xbffffff6, v92
	s_nop 0
	v_cndmask_b32_e32 v85, v201, v85, vcc
	v_cmp_lt_u32_e32 vcc, s71, v93
	v_add_u32_e32 v93, 0xbfffffd6, v92
	s_nop 0
	v_cndmask_b32_e32 v70, v201, v70, vcc
	v_cmp_lt_u32_e32 vcc, s71, v93
	v_add_u32_e32 v93, 0xbffffff5, v92
	s_nop 0
	v_cndmask_b32_e32 v86, v201, v86, vcc
	v_cmp_lt_u32_e32 vcc, s71, v93
	v_add_u32_e32 v93, 0xbfffffd5, v92
	s_nop 0
	v_cndmask_b32_e32 v71, v201, v71, vcc
	v_cmp_lt_u32_e32 vcc, s71, v93
	v_add_u32_e32 v93, 0xbffffff0, v92
	s_nop 0
	v_cndmask_b32_e32 v87, v201, v87, vcc
	v_cmp_lt_u32_e32 vcc, s71, v93
	v_add_u32_e32 v93, 0xbfffffd0, v92
	s_nop 0
	v_cndmask_b32_e32 v72, v201, v72, vcc
	v_cmp_lt_u32_e32 vcc, s71, v93
	v_add_u32_e32 v93, 0xbfffffef, v92
	s_nop 0
	v_cndmask_b32_e32 v88, v201, v88, vcc
	v_cmp_lt_u32_e32 vcc, s71, v93
	v_add_u32_e32 v93, 0xbfffffcf, v92
	s_nop 0
	v_cndmask_b32_e32 v73, v201, v73, vcc
	v_cmp_lt_u32_e32 vcc, s71, v93
	v_add_u32_e32 v93, 0xbfffffee, v92
	s_nop 0
	v_cndmask_b32_e32 v89, v201, v89, vcc
	v_cmp_lt_u32_e32 vcc, s71, v93
	v_add_u32_e32 v93, 0xbfffffce, v92
	s_nop 0
	v_cndmask_b32_e32 v74, v201, v74, vcc
	v_cmp_lt_u32_e32 vcc, s71, v93
	v_add_u32_e32 v93, 0xbfffffed, v92
	s_nop 0
	v_cndmask_b32_e32 v90, v201, v90, vcc
	v_cmp_lt_u32_e32 vcc, s71, v93
	v_add_u32_e32 v93, 0xbfffffcd, v92
	s_nop 0
	v_cndmask_b32_e32 v75, v201, v75, vcc
	v_cmp_lt_u32_e32 vcc, s71, v93
	v_add_u32_e32 v93, 0xbfffffe8, v92
	s_nop 0
	v_cndmask_b32_e32 v91, v201, v91, vcc
	v_cmp_lt_u32_e32 vcc, s71, v93
	v_add_u32_e32 v93, 0xbfffffc8, v92
	s_nop 0
	v_cndmask_b32_e32 v66, v201, v66, vcc
	v_cmp_lt_u32_e32 vcc, s71, v93
	v_add_u32_e32 v93, 0xbfffffe7, v92
	s_nop 0
	v_cndmask_b32_e32 v68, v201, v68, vcc
	v_cmp_lt_u32_e32 vcc, s71, v93
	v_add_u32_e32 v93, 0xbfffffc7, v92
	s_nop 0
	v_cndmask_b32_e32 v67, v201, v67, vcc
	v_cmp_lt_u32_e32 vcc, s71, v93
	v_add_u32_e32 v93, 0xbfffffe6, v92
	s_nop 0
	v_cndmask_b32_e32 v69, v201, v69, vcc
	v_cmp_lt_u32_e32 vcc, s71, v93
	v_add_u32_e32 v93, 0xbfffffc6, v92
	s_nop 0
	v_cndmask_b32_e32 v78, v201, v78, vcc
	v_cmp_lt_u32_e32 vcc, s71, v93
	v_add_u32_e32 v93, 0xbfffffe5, v92
	v_add_u32_e32 v92, 0xbfffffc5, v92
	v_cndmask_b32_e32 v64, v201, v64, vcc
	v_cmp_lt_u32_e32 vcc, s71, v93
	s_nop 1
	v_cndmask_b32_e32 v79, v201, v79, vcc
	v_cmp_lt_u32_e32 vcc, s71, v92
	s_nop 1
	v_cndmask_b32_e32 v65, v201, v65, vcc
